# v49 plus: scan-chain decay-block gcs prefetch, third convert copy batched loads, rmsnorm loops software-pipelined (next row prefetched)
# baseline (speedup 1.0000x reference)
;     ...
;       __syncthreads();
;       {
;         const int nl = tid & 63;
;         const int sc = map_col(d.map, nt * 64 + nl);
; #pragma unroll 4
;         for (int i = 0; i < 16; ++i) {
;           const int kl = (tid >> 6) + 4 * i;
;           const int k = kt * 64 + kl;
;           float v = 0.f;
;           if (sc >= 0) v = d.src[(size_t)k * d.ldsrc + sc];
;           if (d.rowscale) v *= d.rowscale[k];
;           T[kl * 65 + nl] = v;
;         }
;       }
.LBB0_208:
	s_ashr_i32 s8, s46, 31
	s_lshr_b32 s8, s8, 28
	s_add_i32 s8, s46, s8
	s_and_b32 s9, s8, -16
	s_sub_i32 s9, s46, s9
	s_lshl_b32 s8, s8, 2
	s_lshl_b32 s47, s9, 6
	s_andn2_b32 s8, s8, 63
	v_or_b32_e32 v0, s47, v16
	s_cmp_gt_i32 s9, -1
	s_cselect_b64 s[34:35], -1, 0
	v_lshl_add_u64 v[14:15], v[0:1], 2, s[24:25]
	v_add_u32_e32 v0, s8, v2
	s_mov_b32 s9, 0
	v_mov_b32_e32 v19, v18
	s_barrier
	v_mov_b32_e32 v80, 0
	v_mov_b32_e32 v81, 0
	v_mov_b32_e32 v82, 0
	v_mov_b32_e32 v83, 0
	v_mov_b32_e32 v84, 0
	v_mov_b32_e32 v85, 0
	v_mov_b32_e32 v86, 0
	v_mov_b32_e32 v87, 0
	v_mov_b32_e32 v88, 0
	v_mov_b32_e32 v89, 0
	v_mov_b32_e32 v90, 0
	v_mov_b32_e32 v91, 0
	v_mov_b32_e32 v92, 0
	v_mov_b32_e32 v93, 0
	v_mov_b32_e32 v94, 0
	v_mov_b32_e32 v95, 0
	s_andn2_b64 vcc, exec, s[34:35]
	s_cbranch_vccnz .Lcv3_noload
	v_ashrrev_i32_e32 v23, 31, v0
	v_mov_b32_e32 v22, v0
	v_lshlrev_b64 v[22:23], 12, v[22:23]
	v_lshl_add_u64 v[22:23], v[14:15], 0, v[22:23]
	s_mov_b32 s100, 0x4000
	s_mov_b32 s101, 0
	global_load_dword v80, v[22:23], off
	v_lshl_add_u64 v[22:23], v[22:23], 0, s[100:101]
	global_load_dword v81, v[22:23], off
	v_lshl_add_u64 v[22:23], v[22:23], 0, s[100:101]
	global_load_dword v82, v[22:23], off
	v_lshl_add_u64 v[22:23], v[22:23], 0, s[100:101]
	global_load_dword v83, v[22:23], off
	v_lshl_add_u64 v[22:23], v[22:23], 0, s[100:101]
	global_load_dword v84, v[22:23], off
	v_lshl_add_u64 v[22:23], v[22:23], 0, s[100:101]
	global_load_dword v85, v[22:23], off
	v_lshl_add_u64 v[22:23], v[22:23], 0, s[100:101]
	global_load_dword v86, v[22:23], off
	v_lshl_add_u64 v[22:23], v[22:23], 0, s[100:101]
	global_load_dword v87, v[22:23], off
	v_lshl_add_u64 v[22:23], v[22:23], 0, s[100:101]
	global_load_dword v88, v[22:23], off
	v_lshl_add_u64 v[22:23], v[22:23], 0, s[100:101]
	global_load_dword v89, v[22:23], off
	v_lshl_add_u64 v[22:23], v[22:23], 0, s[100:101]
	global_load_dword v90, v[22:23], off
	v_lshl_add_u64 v[22:23], v[22:23], 0, s[100:101]
	global_load_dword v91, v[22:23], off
	v_lshl_add_u64 v[22:23], v[22:23], 0, s[100:101]
	global_load_dword v92, v[22:23], off
	v_lshl_add_u64 v[22:23], v[22:23], 0, s[100:101]
	global_load_dword v93, v[22:23], off
	v_lshl_add_u64 v[22:23], v[22:23], 0, s[100:101]
	global_load_dword v94, v[22:23], off
	v_lshl_add_u64 v[22:23], v[22:23], 0, s[100:101]
	global_load_dword v95, v[22:23], off
.Lcv3_noload:
	s_waitcnt vmcnt(0)
	ds_write_b32 v19, v80
	ds_write_b32 v19, v81 offset:1040
	ds_write_b32 v19, v82 offset:2080
	ds_write_b32 v19, v83 offset:3120
	ds_write_b32 v19, v84 offset:4160
	ds_write_b32 v19, v85 offset:5200
	ds_write_b32 v19, v86 offset:6240
	ds_write_b32 v19, v87 offset:7280
	ds_write_b32 v19, v88 offset:8320
	ds_write_b32 v19, v89 offset:9360
	ds_write_b32 v19, v90 offset:10400
	ds_write_b32 v19, v91 offset:11440
	ds_write_b32 v19, v92 offset:12480
	ds_write_b32 v19, v93 offset:13520
	ds_write_b32 v19, v94 offset:14560
	ds_write_b32 v19, v95 offset:15600
	v_add_u32_e32 v19, 0x4100, v19
	s_mov_b32 s9, 64
	s_branch .LBB0_218
	s_branch .LBB0_210

; DI unsigned pack2(float a, float b) { f2_t v = {a, b}; return __builtin_bit_cast(unsigned, __builtin_convertvector(v, bf2_t)); }
; DI void phase_norm(const float* __restrict__ x, const float* __restrict__ g, bf16_t* __restrict__ dst,
;                            const float* __restrict__ psrc, bf16_t* __restrict__ pdst) {
;     ...
;   for (int r = blockIdx.x * 4 + wave; r < TG; r += gridDim.x * 4) {
;     const float4* xr = (const float4*)(x + (size_t)r * 1024);
;     float4 v[4];
;     float ss = 0.f;
; #pragma unroll
;     for (int i = 0; i < 4; ++i) { v[i] = xr[lane + 64 * i]; ss += v[i].x * v[i].x + v[i].y * v[i].y + v[i].z * v[i].z + v[i].w * v[i].w; }
;     ss = wave_sum(ss);
;     const float rs = rsqrtf(ss * (1.f / 1024.f) + EPS);
; #pragma unroll
;     for (int i = 0; i < 4; ++i) {
;       const float4 gg = ((const float4*)g)[lane + 64 * i];
;       u32x2 o; o.x = pack2(v[i].x * rs * gg.x, v[i].y * rs * gg.y); o.y = pack2(v[i].z * rs * gg.z, v[i].w * rs * gg.w);
;       ((u32x2*)(dst + (size_t)r * 1024))[lane + 64 * i] = o;
;     }
.LBB0_323:
	s_or_b64 exec, exec, s[0:1]
	s_mov_b64 s[8:9], s[94:95]
	s_waitcnt lgkmcnt(0)
	s_barrier
	v_mov_b32 v0, 0
	s_mov_b32 s0, 0x8000
	v_add_u32_e32 v0, v0, v210
	v_ashrrev_i32_e32 v2, 6, v0
	v_add_u32_e32 v18, s93, v2
	v_cmp_gt_i32_e32 vcc, s0, v18
	s_and_saveexec_b64 s[0:1], vcc
	s_movk_i32 s28, 0x7fff
	s_cbranch_execz .LBB0_326
	v_and_b32_e32 v19, 63, v0
	v_and_b32_e32 v0, 64, v225
	v_add_u32_e32 v0, 64, v0
	v_xor_b32_e32 v2, 32, v225
	v_cmp_lt_i32_e32 vcc, v2, v0
	s_load_dwordx4 s[44:47], s[8:9], 0xf8
	s_lshl_b64 s[6:7], s[60:61], 2
	v_cndmask_b32_e32 v2, v225, v2, vcc
	v_lshlrev_b32_e32 v24, 2, v2
	v_xor_b32_e32 v2, 16, v225
	v_cmp_lt_i32_e32 vcc, v2, v0
	s_load_dwordx2 s[8:9], s[8:9], 0x40
	v_readlane_b32 s24, v243, 38
	v_cndmask_b32_e32 v2, v225, v2, vcc
	v_lshlrev_b32_e32 v25, 2, v2
	v_xor_b32_e32 v2, 8, v225
	v_cmp_lt_i32_e32 vcc, v2, v0
	s_waitcnt lgkmcnt(0)
	s_add_u32 s6, s44, s6
	v_readlane_b32 s25, v243, 39
	v_cndmask_b32_e32 v2, v225, v2, vcc
	v_lshlrev_b32_e32 v26, 2, v2
	v_xor_b32_e32 v2, 4, v225
	v_cmp_lt_i32_e32 vcc, v2, v0
	s_addc_u32 s7, s45, s7
	s_lshl_b64 s[24:25], s[24:25], 2
	v_cndmask_b32_e32 v2, v225, v2, vcc
	v_lshlrev_b32_e32 v27, 2, v2
	v_xor_b32_e32 v2, 2, v225
	v_cmp_lt_i32_e32 vcc, v2, v0
	s_add_u32 s8, s8, s24
	s_addc_u32 s9, s9, s25
	v_cndmask_b32_e32 v2, v225, v2, vcc
	v_lshlrev_b32_e32 v28, 2, v2
	v_xor_b32_e32 v2, 1, v225
	v_cmp_lt_i32_e32 vcc, v2, v0
	s_nop 1
	v_cndmask_b32_e32 v0, v225, v2, vcc
	v_lshlrev_b32_e32 v29, 2, v0
	v_lshlrev_b32_e32 v0, 4, v19
	global_load_dwordx4 v[2:5], v0, s[8:9]
	global_load_dwordx4 v[6:9], v0, s[8:9] offset:1024
	global_load_dwordx4 v[10:13], v0, s[8:9] offset:2048
	global_load_dwordx4 v[14:17], v0, s[8:9] offset:3072
	v_lshl_add_u64 v[20:21], s[6:7], 0, v[0:1]
	v_lshlrev_b32_e32 v0, 3, v19
	v_lshl_add_u64 v[22:23], s[46:47], 0, v[0:1]
	s_mov_b64 s[6:7], 0x4000000
	v_lshl_add_u64 v[22:23], v[22:23], 0, s[6:7]
	s_mov_b64 s[6:7], 0
	v_mov_b32_e32 v116, v18
	v_ashrrev_i32_e32 v117, 31, v18
	v_lshlrev_b64 v[116:117], 12, v[116:117]
	v_lshl_add_u64 v[116:117], v[20:21], 0, v[116:117]
	global_load_dwordx4 v[100:103], v[116:117], off
	global_load_dwordx4 v[104:107], v[116:117], off offset:1024
	global_load_dwordx4 v[108:111], v[116:117], off offset:2048
	global_load_dwordx4 v[112:115], v[116:117], off offset:3072
.LBB0_325:
	v_ashrrev_i32_e32 v19, 31, v18
	v_lshlrev_b64 v[34:35], 11, v[18:19]
	v_lshl_add_u64 v[46:47], v[22:23], 0, v[34:35]
	s_waitcnt vmcnt(0)
	v_mov_b32_e32 v30, v100
	v_mov_b32_e32 v31, v101
	v_mov_b32_e32 v32, v102
	v_mov_b32_e32 v33, v103
	v_mov_b32_e32 v34, v104
	v_mov_b32_e32 v35, v105
	v_mov_b32_e32 v36, v106
	v_mov_b32_e32 v37, v107
	v_mov_b32_e32 v58, v108
	v_mov_b32_e32 v59, v109
	v_mov_b32_e32 v60, v110
	v_mov_b32_e32 v61, v111
	v_mov_b32_e32 v62, v112
	v_mov_b32_e32 v63, v113
	v_mov_b32_e32 v64, v114
	v_mov_b32_e32 v65, v115
	v_add_u32_e32 v18, s56, v18
	v_cmp_ge_i32_e32 vcc, s28, v18
	s_cbranch_vccz .Lnp0_skip
	v_mov_b32_e32 v116, v18
	v_ashrrev_i32_e32 v117, 31, v18
	v_lshlrev_b64 v[116:117], 12, v[116:117]
	v_lshl_add_u64 v[116:117], v[20:21], 0, v[116:117]
	global_load_dwordx4 v[100:103], v[116:117], off
	global_load_dwordx4 v[104:107], v[116:117], off offset:1024
	global_load_dwordx4 v[108:111], v[116:117], off offset:2048
	global_load_dwordx4 v[112:115], v[116:117], off offset:3072
.Lnp0_skip:
	v_mov_b32_e32 v48, v31
	v_mov_b32_e32 v44, v30
	v_mov_b32_e32 v49, v35
	v_mov_b32_e32 v45, v34
	v_pk_mul_f32 v[48:49], v[48:49], v[48:49]
	v_mov_b32_e32 v38, v32
	v_mov_b32_e32 v39, v36
	v_pk_fma_f32 v[44:45], v[44:45], v[44:45], v[48:49]
	v_mov_b32_e32 v40, v33
	v_mov_b32_e32 v41, v37
	v_pk_fma_f32 v[38:39], v[38:39], v[38:39], v[44:45]
	s_nop 0
	v_pk_fma_f32 v[48:49], v[40:41], v[40:41], v[38:39]
	v_add_f32_e32 v0, v48, v49
	v_mov_b32_e32 v56, v59
	v_mov_b32_e32 v57, v63
	v_mov_b32_e32 v54, v58
	v_mov_b32_e32 v55, v62
	v_pk_mul_f32 v[56:57], v[56:57], v[56:57]
	v_mov_b32_e32 v50, v60
	v_mov_b32_e32 v51, v64
	v_pk_fma_f32 v[54:55], v[54:55], v[54:55], v[56:57]
	v_mov_b32_e32 v52, v61
	v_mov_b32_e32 v53, v65
	v_pk_fma_f32 v[50:51], v[50:51], v[50:51], v[54:55]
	s_nop 0
	v_pk_fma_f32 v[50:51], v[52:53], v[52:53], v[50:51]
	s_nop 0
	v_add_f32_e32 v0, v0, v50
	v_add_f32_e32 v0, v0, v51
	ds_bpermute_b32 v19, v24, v0
	s_waitcnt lgkmcnt(0)
	v_add_f32_e32 v0, v0, v19
	ds_bpermute_b32 v19, v25, v0
	s_waitcnt lgkmcnt(0)
	v_add_f32_e32 v0, v0, v19
	ds_bpermute_b32 v19, v26, v0
	s_waitcnt lgkmcnt(0)
	v_add_f32_e32 v0, v0, v19
	ds_bpermute_b32 v19, v27, v0
	s_waitcnt lgkmcnt(0)
	v_add_f32_e32 v0, v0, v19
	ds_bpermute_b32 v19, v28, v0
	s_waitcnt lgkmcnt(0)
	v_add_f32_e32 v0, v0, v19
	ds_bpermute_b32 v19, v29, v0
	s_waitcnt lgkmcnt(0)
	v_add_f32_e32 v0, v0, v19
	v_fmamk_f32 v0, v0, 0x3a800000, v216
	v_cmp_gt_f32_e32 vcc, s15, v0
	v_mul_f32_e32 v19, 0x4b800000, v0
	s_nop 0
	v_cndmask_b32_e32 v0, v0, v19, vcc
	v_rsq_f32_e32 v0, v0
	s_nop 0
	v_mul_f32_e32 v19, 0x45800000, v0
	v_cndmask_b32_e32 v0, v0, v19, vcc
	v_pk_mul_f32 v[30:31], v[30:31], v[0:1] op_sel_hi:[1,0]
	v_pk_mul_f32 v[32:33], v[32:33], v[0:1] op_sel_hi:[1,0]
	v_pk_mul_f32 v[30:31], v[2:3], v[30:31]
	v_pk_mul_f32 v[32:33], v[4:5], v[32:33]
	v_cvt_pk_bf16_f32 v30, v30, v31
	v_cvt_pk_bf16_f32 v31, v32, v33
	global_store_dwordx2 v[46:47], v[30:31], off
	v_pk_mul_f32 v[30:31], v[34:35], v[0:1] op_sel_hi:[1,0]
	v_pk_mul_f32 v[32:33], v[36:37], v[0:1] op_sel_hi:[1,0]
	v_pk_mul_f32 v[30:31], v[6:7], v[30:31]
	v_pk_mul_f32 v[32:33], v[8:9], v[32:33]
	v_cvt_pk_bf16_f32 v30, v30, v31
	v_cvt_pk_bf16_f32 v31, v32, v33
	global_store_dwordx2 v[46:47], v[30:31], off offset:512
	v_pk_mul_f32 v[30:31], v[58:59], v[0:1] op_sel_hi:[1,0]
	v_pk_mul_f32 v[32:33], v[60:61], v[0:1] op_sel_hi:[1,0]
	v_pk_mul_f32 v[30:31], v[10:11], v[30:31]
	v_pk_mul_f32 v[32:33], v[12:13], v[32:33]
	v_cvt_pk_bf16_f32 v30, v30, v31
	v_cvt_pk_bf16_f32 v31, v32, v33
	global_store_dwordx2 v[46:47], v[30:31], off offset:1024
	v_pk_mul_f32 v[30:31], v[62:63], v[0:1] op_sel_hi:[1,0]
	v_pk_mul_f32 v[32:33], v[64:65], v[0:1] op_sel_hi:[1,0]
	v_pk_mul_f32 v[30:31], v[14:15], v[30:31]
	v_pk_mul_f32 v[32:33], v[16:17], v[32:33]
	v_cmp_lt_i32_e32 vcc, s28, v18
	v_cvt_pk_bf16_f32 v30, v30, v31
	v_cvt_pk_bf16_f32 v31, v32, v33
	s_or_b64 s[6:7], vcc, s[6:7]
	global_store_dwordx2 v[46:47], v[30:31], off offset:1536
	s_andn2_b64 exec, exec, s[6:7]
	s_cbranch_execnz .LBB0_325

; #define MFMA16(a, b, c) __builtin_amdgcn_mfma_f32_16x16x32_bf16((a), (b), (c), 0, 0, 0)
; DI float bf2f(bf16_t b) { return __uint_as_float(((unsigned)b) << 16); }
; DI void dn_scan_chain(CParams& p, int it, int S, char* lds) {
;     ...
;     {
;       f32x4 QK[4];
; #pragma unroll
;       for (int t = 0; t < 4; ++t) QK[t] = f32x4{0.f, 0.f, 0.f, 0.f};
; #pragma unroll
;       for (int ks = 0; ks < 2; ++ks) {
;         const bf16x8 bfk = *(const bf16x8*)(Kimg + (16 * w + l15) * 72 + 32 * ks + 8 * g4);
; #pragma unroll
;         for (int rt = 0; rt < 4; ++rt) {
;           const bf16x8 afq = *(const bf16x8*)(Qimg + (16 * rt + l15) * 72 + 32 * ks + 8 * g4);
;           QK[rt] = MFMA16(afq, bfk, QK[rt]);
;         }
;       }
;       const float gcj = gcs[e_col];
; #pragma unroll
;       for (int rt = 0; rt < 4; ++rt)
; #pragma unroll
;         for (int r = 0; r < 4; ++r) {
;           const int i = 16 * rt + 4 * g4 + r;
;           const float ee = __expf(fminf(gcs[i] - gcj, 0.f));
;           Iimg[i * 72 + e_col] = f2bf((i >= e_col) ? QK[rt][r] * ee : 0.f);
;         }
;     }
;     __syncthreads();
;     {
;       bf16x8 Bs[2];
; #pragma unroll
;       for (int ks = 0; ks < 2; ++ks)
;         Bs[ks] = pack8(Sd[2 * ks][0], Sd[2 * ks][1], Sd[2 * ks][2], Sd[2 * ks][3], Sd[2 * ks + 1][0], Sd[2 * ks + 1][1],
;                        Sd[2 * ks + 1][2], Sd[2 * ks + 1][3]);
;       f32x4 vn[4], qs[4], iv[4];
; #pragma unroll
;       for (int rt = 0; rt < 4; ++rt) {
; #pragma unroll
;         for (int r = 0; r < 4; ++r) vn[rt][r] = bf2f(Uimg[(16 * rt + 4 * g4 + r) * 72 + e_col]);
.LBB0_616:
	v_and_b32_e32 v68, 15, v52
	v_bfe_u32 v69, v52, 4, 2
	v_lshlrev_b32_e32 v54, 4, v69
	v_mul_u32_u24_e32 v70, 0x90, v68
	v_ashrrev_i32_e32 v0, 2, v52
	v_add3_u32 v67, 16, v54, v70
	v_bfi_b32 v98, -16, v0, v52
	s_waitcnt lgkmcnt(0)
	s_barrier
	v_lshl_add_u32 v96, v69, 4, 16
	ds_read_b128 v[80:83], v96 offset:55296
	ds_read_b128 v[84:87], v96 offset:55360
	ds_read_b128 v[88:91], v96 offset:55424
	ds_read_b128 v[92:95], v96 offset:55488
	ds_read_b128 v[58:61], v67 offset:20736
	ds_read_b128 v[62:65], v67 offset:23040
	v_mul_lo_u32 v0, v98, s12
	v_add_u32_e32 v0, 16, v0
	v_add_u32_e32 v66, v0, v54
	ds_read_b128 v[50:53], v66 offset:27648
	ds_read_b128 v[54:57], v67 offset:18432
	s_waitcnt lgkmcnt(1)
	v_mfma_f32_16x16x32_bf16 v[72:75], v[62:65], v[50:53], 0
	ds_read_b128 v[62:65], v67 offset:25344
	s_movk_i32 s6, 0xff74
	s_waitcnt lgkmcnt(1)
	v_mfma_f32_16x16x32_bf16 v[54:57], v[54:57], v[50:53], 0
	v_mfma_f32_16x16x32_bf16 v[58:61], v[58:61], v[50:53], 0
	s_waitcnt lgkmcnt(0)
	v_mfma_f32_16x16x32_bf16 v[50:53], v[62:65], v[50:53], 0
	ds_read_b128 v[76:79], v66 offset:27712
	ds_read_b128 v[62:65], v67 offset:18496
	s_waitcnt lgkmcnt(0)
	v_mfma_f32_16x16x32_bf16 v[62:65], v[62:65], v[76:79], v[54:57]
	s_nop 2
	ds_read_b128 v[54:57], v67 offset:20800
	s_waitcnt lgkmcnt(0)
	v_mfma_f32_16x16x32_bf16 v[58:61], v[54:57], v[76:79], v[58:61]
	ds_read_b128 v[54:57], v67 offset:23104
	s_waitcnt lgkmcnt(0)
	v_mfma_f32_16x16x32_bf16 v[54:57], v[54:57], v[76:79], v[72:75]
	s_nop 2
	ds_read_b128 v[72:75], v67 offset:25408
	v_mad_u64_u32 v[66:67], s[6:7], v98, s6, v[0:1]
	ds_read_b32 v67, v66 offset:55296
	s_waitcnt lgkmcnt(1)
	v_mfma_f32_16x16x32_bf16 v[50:53], v[72:75], v[76:79], v[50:53]
	v_lshlrev_b32_e32 v0, 2, v69
	v_cmp_ge_i32_e64 s[44:45], v0, v98
	v_mov_b32_e32 v72, 0
	v_lshl_add_u32 v71, v0, 2, 16
	v_mov_b32_e32 v73, 0
	v_lshlrev_b32_e32 v126, 3, v69
	v_add3_u32 v126, 16, v126, v70
	v_mul_u32_u24_e32 v127, 0x240, v69
	v_lshl_add_u32 v128, v98, 1, 16
	v_add_u32_e32 v127, v127, v128
	ds_read_b64 v[130:131], v126 offset:9216
	ds_read_b64 v[132:133], v126 offset:9248
	ds_read_b64 v[138:139], v126 offset:18432
	ds_read_b64 v[140:141], v126 offset:18464
	ds_read_b64 v[134:135], v126 offset:9280
	ds_read_b64 v[136:137], v126 offset:9312
	ds_read_b64 v[142:143], v126 offset:18496
	ds_read_b64 v[144:145], v126 offset:18528
	ds_read_b64 v[146:147], v126 offset:11520
	ds_read_b64 v[148:149], v126 offset:11552
	ds_read_b64 v[154:155], v126 offset:20736
	ds_read_b64 v[156:157], v126 offset:20768
	ds_read_b64 v[150:151], v126 offset:11584
	ds_read_b64 v[152:153], v126 offset:11616
	ds_read_b64 v[158:159], v126 offset:20800
	ds_read_b64 v[160:161], v126 offset:20832
	ds_read_b64 v[162:163], v126 offset:13824
	ds_read_b64 v[164:165], v126 offset:13856
	ds_read_b64 v[170:171], v126 offset:23040
	ds_read_b64 v[172:173], v126 offset:23072
	ds_read_b64 v[166:167], v126 offset:13888
	ds_read_b64 v[168:169], v126 offset:13920
	ds_read_b64 v[174:175], v126 offset:23104
	ds_read_b64 v[176:177], v126 offset:23136
	ds_read_b64 v[178:179], v126 offset:16128
	ds_read_b64 v[180:181], v126 offset:16160
	ds_read_b64 v[186:187], v126 offset:25344
	ds_read_b64 v[188:189], v126 offset:25376
	ds_read_b64 v[182:183], v126 offset:16192
	ds_read_b64 v[184:185], v126 offset:16224
	ds_read_b64 v[190:191], v126 offset:25408
	ds_read_b64 v[192:193], v126 offset:25440
	ds_read_u16 v194, v127 offset:0
	ds_read_u16 v195, v127 offset:144
	ds_read_u16 v196, v127 offset:288
	ds_read_u16 v197, v127 offset:432
	ds_read_u16 v198, v127 offset:2304
	ds_read_u16 v199, v127 offset:2448
	ds_read_u16 v200, v127 offset:2592
	ds_read_u16 v201, v127 offset:2736
	ds_read_u16 v202, v127 offset:4608
	ds_read_u16 v203, v127 offset:4752
	ds_read_u16 v204, v127 offset:4896
	ds_read_u16 v205, v127 offset:5040
	ds_read_u16 v206, v127 offset:6912
	ds_read_u16 v207, v127 offset:7056
	ds_read_u16 v208, v127 offset:7200
	ds_read_u16 v209, v127 offset:7344
	s_waitcnt lgkmcnt(0)
	s_and_saveexec_b64 s[6:7], s[44:45]
	s_cbranch_execz .LBB0_618
	v_sub_f32_e32 v73, v80, v67
	v_min_f32_e32 v73, 0, v73
	v_mul_f32_e32 v73, 0x3fb8aa3b, v73
	v_exp_f32_e32 v73, v73
	s_nop 0
	v_mul_f32_e32 v62, v62, v73
	v_cvt_pk_bf16_f32 v73, v62, s0
.LBB0_618:
	s_or_b64 exec, exec, s[6:7]
	v_lshlrev_b32_e32 v62, 1, v98
	v_sub_u32_e32 v66, v66, v62
	v_or_b32_e32 v124, 1, v0
	v_mad_u32_u24 v62, v69, s21, v66
	v_cmp_ge_i32_e64 s[44:45], v124, v98
	ds_write_b16 v62, v73 offset:46080
	s_and_saveexec_b64 s[6:7], s[44:45]
	s_cbranch_execz .LBB0_620
	v_sub_f32_e32 v62, v81, v67
	v_min_f32_e32 v62, 0, v62
	v_mul_f32_e32 v62, 0x3fb8aa3b, v62
	v_exp_f32_e32 v62, v62
	s_nop 0
	v_mul_f32_e32 v62, v63, v62
	v_cvt_pk_bf16_f32 v72, v62, s0
.LBB0_620:
	s_or_b64 exec, exec, s[6:7]
	v_mad_u32_u24 v62, v124, s12, v66
	v_or_b32_e32 v123, 2, v0
	ds_write_b16 v62, v72 offset:46080
	v_cmp_ge_i32_e64 s[44:45], v123, v98
	v_mov_b32_e32 v72, 0
	v_mov_b32_e32 v73, 0
	s_and_saveexec_b64 s[6:7], s[44:45]
	s_cbranch_execz .LBB0_622
	v_sub_f32_e32 v62, v82, v67
	v_min_f32_e32 v62, 0, v62
	v_mul_f32_e32 v62, 0x3fb8aa3b, v62
	v_exp_f32_e32 v62, v62
	s_nop 0
	v_mul_f32_e32 v62, v64, v62
	v_cvt_pk_bf16_f32 v73, v62, s0
; DI void dn_scan_chain(CParams& p, int it, int S, char* lds) {
;     ...
;       const float gcj = gcs[e_col];
; #pragma unroll
;       for (int rt = 0; rt < 4; ++rt)
; #pragma unroll
;         for (int r = 0; r < 4; ++r) {
;           const int i = 16 * rt + 4 * g4 + r;
;           const float ee = __expf(fminf(gcs[i] - gcj, 0.f));
;           Iimg[i * 72 + e_col] = f2bf((i >= e_col) ? QK[rt][r] * ee : 0.f);
;         }
.LBB0_622:
	s_or_b64 exec, exec, s[6:7]
	v_mul_u32_u24_e32 v62, 0x90, v124
	v_or_b32_e32 v121, 3, v0
	v_add_u32_e32 v63, v62, v66
	v_cmp_ge_i32_e64 s[44:45], v121, v98
	ds_write_b16 v63, v73 offset:46224
	s_and_saveexec_b64 s[6:7], s[44:45]
	s_cbranch_execz .LBB0_624
	v_sub_f32_e32 v64, v83, v67
	v_min_f32_e32 v64, 0, v64
	v_mul_f32_e32 v64, 0x3fb8aa3b, v64
	v_exp_f32_e32 v64, v64
	s_nop 0
	v_mul_f32_e32 v64, v65, v64
	v_cvt_pk_bf16_f32 v72, v64, s0
.LBB0_624:
	s_or_b64 exec, exec, s[6:7]
	v_or_b32_e32 v118, 16, v0
	v_cmp_ge_i32_e64 s[44:45], v118, v98
	v_mov_b32_e32 v64, 0
	v_mov_b32_e32 v65, 0
	ds_write_b16 v63, v72 offset:46368
	s_and_saveexec_b64 s[6:7], s[44:45]
	s_cbranch_execz .LBB0_626
	v_sub_f32_e32 v65, v84, v67
	v_min_f32_e32 v65, 0, v65
	v_mul_f32_e32 v65, 0x3fb8aa3b, v65
	v_exp_f32_e32 v65, v65
	s_nop 0
	v_mul_f32_e32 v58, v58, v65
	v_cvt_pk_bf16_f32 v65, v58, s0
.LBB0_626:
	s_or_b64 exec, exec, s[6:7]
	v_or_b32_e32 v119, 17, v0
	v_cmp_ge_i32_e64 s[44:45], v119, v98
	ds_write_b16 v63, v65 offset:48240
	s_and_saveexec_b64 s[6:7], s[44:45]
	s_cbranch_execz .LBB0_628
	v_sub_f32_e32 v58, v85, v67
	v_min_f32_e32 v58, 0, v58
	v_mul_f32_e32 v58, 0x3fb8aa3b, v58
	v_exp_f32_e32 v58, v58
	s_nop 0
	v_mul_f32_e32 v58, v59, v58
	v_cvt_pk_bf16_f32 v64, v58, s0
.LBB0_628:
	s_or_b64 exec, exec, s[6:7]
	v_or_b32_e32 v120, 18, v0
	v_cmp_ge_i32_e64 s[44:45], v120, v98
	v_mov_b32_e32 v58, 0
	v_mov_b32_e32 v59, 0
	ds_write_b16 v63, v64 offset:48384
	s_and_saveexec_b64 s[6:7], s[44:45]
	s_cbranch_execz .LBB0_630
	v_sub_f32_e32 v59, v86, v67
	v_min_f32_e32 v59, 0, v59
	v_mul_f32_e32 v59, 0x3fb8aa3b, v59
	v_exp_f32_e32 v59, v59
	s_nop 0
	v_mul_f32_e32 v59, v60, v59
	v_cvt_pk_bf16_f32 v59, v59, s0
.LBB0_630:
	s_or_b64 exec, exec, s[6:7]
	v_or_b32_e32 v122, 19, v0
	v_cmp_ge_i32_e64 s[44:45], v122, v98
	ds_write_b16 v63, v59 offset:48528
	s_and_saveexec_b64 s[6:7], s[44:45]
	s_cbranch_execz .LBB0_632
	v_sub_f32_e32 v58, v87, v67
	v_min_f32_e32 v58, 0, v58
	v_mul_f32_e32 v58, 0x3fb8aa3b, v58
	v_exp_f32_e32 v58, v58
	s_nop 0
	v_mul_f32_e32 v58, v61, v58
	v_cvt_pk_bf16_f32 v58, v58, s0
.LBB0_632:
	s_or_b64 exec, exec, s[6:7]
	v_or_b32_e32 v116, 32, v0
	ds_write_b16 v63, v58 offset:48672
	v_cmp_ge_i32_e64 s[44:45], v116, v98
	v_mov_b32_e32 v58, 0
	v_mov_b32_e32 v59, 0
	s_and_saveexec_b64 s[6:7], s[44:45]
	s_cbranch_execz .LBB0_634
	v_sub_f32_e32 v59, v88, v67
	v_min_f32_e32 v59, 0, v59
	v_mul_f32_e32 v59, 0x3fb8aa3b, v59
	v_exp_f32_e32 v59, v59
	s_nop 0
	v_mul_f32_e32 v54, v54, v59
	v_cvt_pk_bf16_f32 v59, v54, s0
.LBB0_634:
	s_or_b64 exec, exec, s[6:7]
	v_or_b32_e32 v115, 33, v0
	v_cmp_ge_i32_e64 s[44:45], v115, v98
	ds_write_b16 v63, v59 offset:50544
	s_and_saveexec_b64 s[6:7], s[44:45]
	s_cbranch_execz .LBB0_636
	v_sub_f32_e32 v54, v89, v67
	v_min_f32_e32 v54, 0, v54
	v_mul_f32_e32 v54, 0x3fb8aa3b, v54
	v_exp_f32_e32 v54, v54
	s_nop 0
	v_mul_f32_e32 v54, v55, v54
	v_cvt_pk_bf16_f32 v58, v54, s0
.LBB0_636:
	s_or_b64 exec, exec, s[6:7]
	v_or_b32_e32 v114, 34, v0
	v_cmp_ge_i32_e64 s[44:45], v114, v98
	v_mov_b32_e32 v54, 0
	v_mov_b32_e32 v55, 0
	ds_write_b16 v63, v58 offset:50688
	s_and_saveexec_b64 s[6:7], s[44:45]
	s_cbranch_execz .LBB0_638
	v_sub_f32_e32 v55, v90, v67
	v_min_f32_e32 v55, 0, v55
	v_mul_f32_e32 v55, 0x3fb8aa3b, v55
	v_exp_f32_e32 v55, v55
	s_nop 0
	v_mul_f32_e32 v55, v56, v55
	v_cvt_pk_bf16_f32 v55, v55, s0
.LBB0_638:
	s_or_b64 exec, exec, s[6:7]
	v_or_b32_e32 v113, 35, v0
	v_cmp_ge_i32_e64 s[44:45], v113, v98
	ds_write_b16 v63, v55 offset:50832
	s_and_saveexec_b64 s[6:7], s[44:45]
	s_cbranch_execz .LBB0_640
	v_sub_f32_e32 v54, v91, v67
	v_min_f32_e32 v54, 0, v54
	v_mul_f32_e32 v54, 0x3fb8aa3b, v54
	v_exp_f32_e32 v54, v54
	s_nop 0
	v_mul_f32_e32 v54, v57, v54
	v_cvt_pk_bf16_f32 v54, v54, s0
.LBB0_640:
	s_or_b64 exec, exec, s[6:7]
	v_or_b32_e32 v112, 48, v0
	ds_write_b16 v63, v54 offset:50976
	v_cmp_ge_i32_e64 s[44:45], v112, v98
	v_mov_b32_e32 v54, 0
	v_mov_b32_e32 v55, 0
	s_and_saveexec_b64 s[6:7], s[44:45]
	s_cbranch_execz .LBB0_642
	v_sub_f32_e32 v55, v92, v67
	v_min_f32_e32 v55, 0, v55
	v_mul_f32_e32 v55, 0x3fb8aa3b, v55
	v_exp_f32_e32 v55, v55
	s_nop 0
	v_mul_f32_e32 v50, v50, v55
	v_cvt_pk_bf16_f32 v55, v50, s0
.LBB0_642:
	s_or_b64 exec, exec, s[6:7]
	v_or_b32_e32 v111, 49, v0
	v_cmp_ge_i32_e64 s[44:45], v111, v98
	ds_write_b16 v63, v55 offset:52848
	s_and_saveexec_b64 s[6:7], s[44:45]
	s_cbranch_execz .LBB0_644
	v_sub_f32_e32 v50, v93, v67
	v_min_f32_e32 v50, 0, v50
	v_mul_f32_e32 v50, 0x3fb8aa3b, v50
	v_exp_f32_e32 v50, v50
	s_nop 0
	v_mul_f32_e32 v50, v51, v50
	v_cvt_pk_bf16_f32 v54, v50, s0
.LBB0_644:
	s_or_b64 exec, exec, s[6:7]
	v_or_b32_e32 v109, 50, v0
	v_cmp_ge_i32_e64 s[44:45], v109, v98
	v_mov_b32_e32 v50, 0
	v_mov_b32_e32 v51, 0
	ds_write_b16 v63, v54 offset:52992
	s_and_saveexec_b64 s[6:7], s[44:45]
	s_cbranch_execz .LBB0_646
	v_sub_f32_e32 v51, v94, v67
	v_min_f32_e32 v51, 0, v51
	v_mul_f32_e32 v51, 0x3fb8aa3b, v51
	v_exp_f32_e32 v51, v51
	s_nop 0
	v_mul_f32_e32 v51, v52, v51
	v_cvt_pk_bf16_f32 v51, v51, s0
.LBB0_646:
	s_or_b64 exec, exec, s[6:7]
	v_or_b32_e32 v110, 51, v0
	v_cmp_ge_i32_e64 s[44:45], v110, v98
	ds_write_b16 v63, v51 offset:53136
	s_and_saveexec_b64 s[6:7], s[44:45]
	s_cbranch_execz .LBB0_609
	v_sub_f32_e32 v50, v95, v67
	v_min_f32_e32 v50, 0, v50
	v_mul_f32_e32 v50, 0x3fb8aa3b, v50
	v_exp_f32_e32 v50, v50
	s_nop 0
	v_mul_f32_e32 v50, v53, v50
	v_cvt_pk_bf16_f32 v50, v50, s0
	s_branch .LBB0_609

; DI int opq() { int z; asm volatile("v_mov_b32 %0, 0" : "=v"(z)); return z; }
; DI void phase_norm(const float* __restrict__ x, const float* __restrict__ g, bf16_t* __restrict__ dst,
;                            const float* __restrict__ psrc, bf16_t* __restrict__ pdst) {
;   const int tidq = threadIdx.x + opq(); const int wave = tidq >> 6, lane = tidq & 63;
;   for (int r = blockIdx.x * 4 + wave; r < TG; r += gridDim.x * 4) {
;     const float4* xr = (const float4*)(x + (size_t)r * 1024);
;     float4 v[4];
;     float ss = 0.f;
; #pragma unroll
;     for (int i = 0; i < 4; ++i) { v[i] = xr[lane + 64 * i]; ss += v[i].x * v[i].x + v[i].y * v[i].y + v[i].z * v[i].z + v[i].w * v[i].w; }
.LBB0_1067:
	s_or_b64 exec, exec, s[0:1]
	s_mov_b64 s[8:9], s[94:95]
	s_waitcnt lgkmcnt(0)
	s_barrier
	v_mov_b32 v0, 0
	s_mov_b32 s0, 0x8000
	v_add_u32_e32 v0, v0, v210
	v_ashrrev_i32_e32 v2, 6, v0
	v_add_u32_e32 v18, s93, v2
	v_cmp_gt_i32_e32 vcc, s0, v18
	s_and_saveexec_b64 s[0:1], vcc
	s_movk_i32 s28, 0x7fff
	s_cbranch_execz .LBB0_1070
	v_and_b32_e32 v19, 63, v0
	v_and_b32_e32 v0, 64, v225
	v_add_u32_e32 v0, 64, v0
	v_xor_b32_e32 v2, 32, v225
	v_cmp_lt_i32_e32 vcc, v2, v0
	s_load_dwordx4 s[44:47], s[8:9], 0xf8
	s_lshl_b64 s[6:7], s[58:59], 2
	v_cndmask_b32_e32 v2, v225, v2, vcc
	v_lshlrev_b32_e32 v24, 2, v2
	v_xor_b32_e32 v2, 16, v225
	v_cmp_lt_i32_e32 vcc, v2, v0
	s_load_dwordx2 s[8:9], s[8:9], 0xb8
	v_readlane_b32 s24, v243, 38
	v_cndmask_b32_e32 v2, v225, v2, vcc
	v_lshlrev_b32_e32 v25, 2, v2
	v_xor_b32_e32 v2, 8, v225
	v_cmp_lt_i32_e32 vcc, v2, v0
	s_waitcnt lgkmcnt(0)
	s_add_u32 s6, s44, s6
	v_readlane_b32 s25, v243, 39
	v_cndmask_b32_e32 v2, v225, v2, vcc
	v_lshlrev_b32_e32 v26, 2, v2
	v_xor_b32_e32 v2, 4, v225
	v_cmp_lt_i32_e32 vcc, v2, v0
	s_addc_u32 s7, s45, s7
	s_lshl_b64 s[24:25], s[24:25], 2
	v_cndmask_b32_e32 v2, v225, v2, vcc
	v_lshlrev_b32_e32 v27, 2, v2
	v_xor_b32_e32 v2, 2, v225
	v_cmp_lt_i32_e32 vcc, v2, v0
	s_add_u32 s8, s8, s24
	s_addc_u32 s9, s9, s25
	v_cndmask_b32_e32 v2, v225, v2, vcc
	v_lshlrev_b32_e32 v28, 2, v2
	v_xor_b32_e32 v2, 1, v225
	v_cmp_lt_i32_e32 vcc, v2, v0
	s_nop 1
	v_cndmask_b32_e32 v0, v225, v2, vcc
	v_lshlrev_b32_e32 v29, 2, v0
	v_lshlrev_b32_e32 v0, 4, v19
	global_load_dwordx4 v[2:5], v0, s[8:9]
	global_load_dwordx4 v[6:9], v0, s[8:9] offset:1024
	global_load_dwordx4 v[10:13], v0, s[8:9] offset:2048
	global_load_dwordx4 v[14:17], v0, s[8:9] offset:3072
	v_lshl_add_u64 v[20:21], s[6:7], 0, v[0:1]
	v_lshlrev_b32_e32 v0, 3, v19
	v_lshl_add_u64 v[22:23], s[46:47], 0, v[0:1]
	s_mov_b64 s[6:7], 0x4000000
	v_lshl_add_u64 v[22:23], v[22:23], 0, s[6:7]
	s_mov_b64 s[6:7], 0
	v_mov_b32_e32 v116, v18
	v_ashrrev_i32_e32 v117, 31, v18
	v_lshlrev_b64 v[116:117], 12, v[116:117]
	v_lshl_add_u64 v[116:117], v[20:21], 0, v[116:117]
	global_load_dwordx4 v[100:103], v[116:117], off
	global_load_dwordx4 v[104:107], v[116:117], off offset:1024
	global_load_dwordx4 v[108:111], v[116:117], off offset:2048
	global_load_dwordx4 v[112:115], v[116:117], off offset:3072

; DI unsigned pack2(float a, float b) { f2_t v = {a, b}; return __builtin_bit_cast(unsigned, __builtin_convertvector(v, bf2_t)); }
; DI void phase_norm(const float* __restrict__ x, const float* __restrict__ g, bf16_t* __restrict__ dst,
;                            const float* __restrict__ psrc, bf16_t* __restrict__ pdst) {
;     ...
;   for (int r = blockIdx.x * 4 + wave; r < TG; r += gridDim.x * 4) {
;     const float4* xr = (const float4*)(x + (size_t)r * 1024);
;     float4 v[4];
;     float ss = 0.f;
; #pragma unroll
;     for (int i = 0; i < 4; ++i) { v[i] = xr[lane + 64 * i]; ss += v[i].x * v[i].x + v[i].y * v[i].y + v[i].z * v[i].z + v[i].w * v[i].w; }
;     ss = wave_sum(ss);
;     const float rs = rsqrtf(ss * (1.f / 1024.f) + EPS);
; #pragma unroll
;     for (int i = 0; i < 4; ++i) {
;       const float4 gg = ((const float4*)g)[lane + 64 * i];
;       u32x2 o; o.x = pack2(v[i].x * rs * gg.x, v[i].y * rs * gg.y); o.y = pack2(v[i].z * rs * gg.z, v[i].w * rs * gg.w);
;       ((u32x2*)(dst + (size_t)r * 1024))[lane + 64 * i] = o;
;     }
.LBB0_1295:
	v_mov_b32 v0, 0
	s_mov_b32 s6, 0x8000
	v_add_u32_e32 v0, v0, v210
	v_ashrrev_i32_e32 v2, 6, v0
	v_add_u32_e32 v18, s93, v2
	v_cmp_gt_i32_e32 vcc, s6, v18
	s_and_saveexec_b64 s[6:7], vcc
	s_movk_i32 s38, 0x7fff
	s_cbranch_execz .LBB0_1298
	s_load_dwordx2 s[34:35], s[0:1], 0x20
	s_lshl_b32 s28, s24, 10
	s_lshl_b64 s[24:25], s[28:29], 2
	v_and_b32_e32 v19, 63, v0
	v_lshlrev_b32_e32 v0, 4, v19
	s_waitcnt lgkmcnt(0)
	s_add_u32 s24, s34, s24
	s_addc_u32 s25, s35, s25
	global_load_dwordx4 v[2:5], v0, s[24:25]
	global_load_dwordx4 v[6:9], v0, s[24:25] offset:1024
	global_load_dwordx4 v[10:13], v0, s[24:25] offset:2048
	global_load_dwordx4 v[14:17], v0, s[24:25] offset:3072
	v_and_b32_e32 v20, 64, v225
	v_add_u32_e32 v20, 64, v20
	v_xor_b32_e32 v21, 32, v225
	v_cmp_lt_i32_e32 vcc, v21, v20
	s_mov_b64 s[24:25], 0
	s_nop 0
	v_cndmask_b32_e32 v21, v225, v21, vcc
	v_lshlrev_b32_e32 v24, 2, v21
	v_xor_b32_e32 v21, 16, v225
	v_cmp_lt_i32_e32 vcc, v21, v20
	s_nop 1
	v_cndmask_b32_e32 v21, v225, v21, vcc
	v_lshlrev_b32_e32 v25, 2, v21
	v_xor_b32_e32 v21, 8, v225
	v_cmp_lt_i32_e32 vcc, v21, v20
	s_nop 1
	v_cndmask_b32_e32 v21, v225, v21, vcc
	v_lshlrev_b32_e32 v26, 2, v21
	v_xor_b32_e32 v21, 4, v225
	v_cmp_lt_i32_e32 vcc, v21, v20
	s_nop 1
	v_cndmask_b32_e32 v21, v225, v21, vcc
	v_lshlrev_b32_e32 v27, 2, v21
	v_xor_b32_e32 v21, 2, v225
	v_cmp_lt_i32_e32 vcc, v21, v20
	s_nop 1
	v_cndmask_b32_e32 v21, v225, v21, vcc
	v_lshlrev_b32_e32 v28, 2, v21
	v_xor_b32_e32 v21, 1, v225
	v_cmp_lt_i32_e32 vcc, v21, v20
	s_nop 1
	v_cndmask_b32_e32 v20, v225, v21, vcc
	v_lshlrev_b32_e32 v29, 2, v20
	v_lshl_add_u64 v[20:21], s[8:9], 0, v[0:1]
	v_lshlrev_b32_e32 v0, 3, v19
	v_lshl_add_u64 v[22:23], s[46:47], 0, v[0:1]
	s_mov_b64 s[8:9], 0x1a000000
	v_lshl_add_u64 v[22:23], v[22:23], 0, s[8:9]
	v_mov_b32_e32 v116, v18
	v_ashrrev_i32_e32 v117, 31, v18
	v_lshlrev_b64 v[116:117], 12, v[116:117]
	v_lshl_add_u64 v[116:117], v[20:21], 0, v[116:117]
	global_load_dwordx4 v[100:103], v[116:117], off
	global_load_dwordx4 v[104:107], v[116:117], off offset:1024
	global_load_dwordx4 v[108:111], v[116:117], off offset:2048
	global_load_dwordx4 v[112:115], v[116:117], off offset:3072
.LBB0_1297:
	v_ashrrev_i32_e32 v19, 31, v18
	v_lshlrev_b64 v[34:35], 11, v[18:19]
	v_lshl_add_u64 v[46:47], v[22:23], 0, v[34:35]
	s_waitcnt vmcnt(0)
	v_mov_b32_e32 v30, v100
	v_mov_b32_e32 v31, v101
	v_mov_b32_e32 v32, v102
	v_mov_b32_e32 v33, v103
	v_mov_b32_e32 v34, v104
	v_mov_b32_e32 v35, v105
	v_mov_b32_e32 v36, v106
	v_mov_b32_e32 v37, v107
	v_mov_b32_e32 v58, v108
	v_mov_b32_e32 v59, v109
	v_mov_b32_e32 v60, v110
	v_mov_b32_e32 v61, v111
	v_mov_b32_e32 v62, v112
	v_mov_b32_e32 v63, v113
	v_mov_b32_e32 v64, v114
	v_mov_b32_e32 v65, v115
	v_add_u32_e32 v18, s56, v18
	v_cmp_ge_i32_e32 vcc, s38, v18
	s_cbranch_vccz .LnpC_skip
	v_mov_b32_e32 v116, v18
	v_ashrrev_i32_e32 v117, 31, v18
	v_lshlrev_b64 v[116:117], 12, v[116:117]
	v_lshl_add_u64 v[116:117], v[20:21], 0, v[116:117]
	global_load_dwordx4 v[100:103], v[116:117], off
	global_load_dwordx4 v[104:107], v[116:117], off offset:1024
	global_load_dwordx4 v[108:111], v[116:117], off offset:2048
	global_load_dwordx4 v[112:115], v[116:117], off offset:3072
.LnpC_skip:
	v_mov_b32_e32 v48, v31
	v_mov_b32_e32 v44, v30
	v_mov_b32_e32 v49, v35
	v_mov_b32_e32 v45, v34
	v_pk_mul_f32 v[48:49], v[48:49], v[48:49]
	v_mov_b32_e32 v38, v32
	v_mov_b32_e32 v39, v36
	v_pk_fma_f32 v[44:45], v[44:45], v[44:45], v[48:49]
	v_mov_b32_e32 v40, v33
	v_mov_b32_e32 v41, v37
	v_pk_fma_f32 v[38:39], v[38:39], v[38:39], v[44:45]
	s_nop 0
	v_pk_fma_f32 v[48:49], v[40:41], v[40:41], v[38:39]
	v_add_f32_e32 v0, v48, v49
	v_mov_b32_e32 v56, v59
	v_mov_b32_e32 v57, v63
	v_mov_b32_e32 v54, v58
	v_mov_b32_e32 v55, v62
	v_pk_mul_f32 v[56:57], v[56:57], v[56:57]
	v_mov_b32_e32 v50, v60
	v_mov_b32_e32 v51, v64
	v_pk_fma_f32 v[54:55], v[54:55], v[54:55], v[56:57]
	v_mov_b32_e32 v52, v61
	v_mov_b32_e32 v53, v65
	v_pk_fma_f32 v[50:51], v[50:51], v[50:51], v[54:55]
	s_nop 0
	v_pk_fma_f32 v[50:51], v[52:53], v[52:53], v[50:51]
	s_nop 0
	v_add_f32_e32 v0, v0, v50
	v_add_f32_e32 v0, v0, v51
	ds_bpermute_b32 v19, v24, v0
	s_waitcnt lgkmcnt(0)
	v_add_f32_e32 v0, v0, v19
	ds_bpermute_b32 v19, v25, v0
	s_waitcnt lgkmcnt(0)
	v_add_f32_e32 v0, v0, v19
	ds_bpermute_b32 v19, v26, v0
	s_waitcnt lgkmcnt(0)
	v_add_f32_e32 v0, v0, v19
	ds_bpermute_b32 v19, v27, v0
	s_waitcnt lgkmcnt(0)
	v_add_f32_e32 v0, v0, v19
	ds_bpermute_b32 v19, v28, v0
	s_waitcnt lgkmcnt(0)
	v_add_f32_e32 v0, v0, v19
	ds_bpermute_b32 v19, v29, v0
	s_waitcnt lgkmcnt(0)
	v_add_f32_e32 v0, v0, v19
	v_fmamk_f32 v0, v0, 0x3a800000, v216
	v_cmp_gt_f32_e32 vcc, s15, v0
	v_mul_f32_e32 v19, 0x4b800000, v0
	s_nop 0
	v_cndmask_b32_e32 v0, v0, v19, vcc
	v_rsq_f32_e32 v0, v0
	s_nop 0
	v_mul_f32_e32 v19, 0x45800000, v0
	v_cndmask_b32_e32 v0, v0, v19, vcc
	v_pk_mul_f32 v[30:31], v[30:31], v[0:1] op_sel_hi:[1,0]
	v_pk_mul_f32 v[32:33], v[32:33], v[0:1] op_sel_hi:[1,0]
	v_pk_mul_f32 v[30:31], v[2:3], v[30:31]
	v_pk_mul_f32 v[32:33], v[4:5], v[32:33]
	v_cvt_pk_bf16_f32 v30, v30, v31
	v_cvt_pk_bf16_f32 v31, v32, v33
	global_store_dwordx2 v[46:47], v[30:31], off
	v_pk_mul_f32 v[30:31], v[34:35], v[0:1] op_sel_hi:[1,0]
	v_pk_mul_f32 v[32:33], v[36:37], v[0:1] op_sel_hi:[1,0]
	v_pk_mul_f32 v[30:31], v[6:7], v[30:31]
	v_pk_mul_f32 v[32:33], v[8:9], v[32:33]
	v_cvt_pk_bf16_f32 v30, v30, v31
	v_cvt_pk_bf16_f32 v31, v32, v33
	global_store_dwordx2 v[46:47], v[30:31], off offset:512
	v_pk_mul_f32 v[30:31], v[58:59], v[0:1] op_sel_hi:[1,0]
	v_pk_mul_f32 v[32:33], v[60:61], v[0:1] op_sel_hi:[1,0]
	v_pk_mul_f32 v[30:31], v[10:11], v[30:31]
	v_pk_mul_f32 v[32:33], v[12:13], v[32:33]
	v_cvt_pk_bf16_f32 v30, v30, v31
	v_cvt_pk_bf16_f32 v31, v32, v33
	global_store_dwordx2 v[46:47], v[30:31], off offset:1024
	v_pk_mul_f32 v[30:31], v[62:63], v[0:1] op_sel_hi:[1,0]
	v_pk_mul_f32 v[32:33], v[64:65], v[0:1] op_sel_hi:[1,0]
	v_pk_mul_f32 v[30:31], v[14:15], v[30:31]
	v_pk_mul_f32 v[32:33], v[16:17], v[32:33]
	v_cmp_lt_i32_e32 vcc, s38, v18
	v_cvt_pk_bf16_f32 v30, v30, v31
	v_cvt_pk_bf16_f32 v31, v32, v33
	s_or_b64 s[24:25], vcc, s[24:25]
	global_store_dwordx2 v[46:47], v[30:31], off offset:1536
	s_andn2_b64 exec, exec, s[24:25]
	s_cbranch_execnz .LBB0_1297
